# v16 + lru1 gate tile prefetched by the same workgroup's lru0 (M1) with direct HBM->LDS loads; lru1's own fill (8 loads + 8 ds_write_b128 behind a second round trip) dropped
# baseline (speedup 1.0000x reference)
; #define LAS __attribute__((address_space(3)))
; __device__ __forceinline__ int opaque_tid() { int t = threadIdx.x; asm volatile("" : "+v"(t)); return t; }
; __device__ __forceinline__ void lru_carries(const Args& a, LAS float* carry, int tt, const Tile& T) {
;     const int tid = opaque_tid(), dir = tid >> 8, ch = tid & 255;
;     const float* SUM = (const float*)(a.ws + WS_SUM);
;     int pos;
;     if (tt < 128) { const int i = tt & 31; pos = 2 + (dir ? 31 - i : i); } else { const int jj = (tt - 128) & 1; pos = dir ? 1 - jj : jj; }
;     f32x2 sm[33];
; #pragma unroll
;     for (int p = 0; p < 33; ++p) {
;         const int pc = p < pos ? p : 0;
;         int t2;
;         if (pc < 2) t2 = 128 + 2 * T.b + (dir ? 1 - pc : pc); else t2 = 32 * T.b + (dir ? 31 - (pc - 2) : (pc - 2));
;         sm[p] = *(const f32x2*)(SUM + ((size_t)(t2 * 2 + dir) * 256 + ch) * 2);
;     }
.LBB0_525:
	v_lshlrev_b32_e32 v66, 3, v100
	v_readlane_b32 s0, v253, 43
	v_and_b32_e32 v206, 0x7f8, v66
	v_readlane_b32 s1, v253, 44
	v_cmp_lt_u32_e64 s[4:5], 1, v101
	s_lshl_b32 s72, s36, 5
	v_lshl_add_u64 v[66:67], s[0:1], 0, v[206:207]
	s_lshl_b32 s0, s36, 1
	s_add_i32 s38, s0, 0x80
	s_movk_i32 s0, 0xff
	v_cmp_lt_u32_e64 s[0:1], s0, v100
	s_xor_b64 s[36:37], s[0:1], s[4:5]
	v_cndmask_b32_e64 v70, 0, 1, s[36:37]
	v_cndmask_b32_e64 v68, 0, 1, s[0:1]
	v_cndmask_b32_e64 v72, 0, 31, s[0:1]
	v_or_b32_e32 v135, s38, v68
	v_or_b32_e32 v72, s72, v72
	v_cmp_lt_u32_e64 s[36:37], 2, v101
	v_ashrrev_i32_e32 v134, 8, v100
	v_or_b32_e32 v70, s38, v70
	v_cndmask_b32_e64 v72, v135, v72, s[36:37]
	v_lshl_add_u32 v72, v72, 1, v134
	v_ashrrev_i32_e32 v73, 31, v72
	v_lshlrev_b64 v[72:73], 11, v[72:73]
	v_lshl_add_u64 v[76:77], v[66:67], 0, v[72:73]
	v_cndmask_b32_e64 v72, 1, 30, s[0:1]
	v_or_b32_e32 v72, s72, v72
	v_cmp_gt_u32_e64 s[38:39], 4, v101
	v_lshl_add_u32 v68, v135, 1, v134
	v_lshl_add_u32 v70, v70, 1, v134
	v_cndmask_b32_e64 v72, v72, v135, s[38:39]
	v_cndmask_b32_e64 v80, 4, 27, s[0:1]
	v_ashrrev_i32_e32 v69, 31, v68
	v_ashrrev_i32_e32 v71, 31, v70
	v_lshl_add_u32 v72, v72, 1, v134
	v_or_b32_e32 v80, s72, v80
	v_cmp_gt_u32_e64 s[44:45], 7, v101
	v_lshlrev_b64 v[68:69], 11, v[68:69]
	v_lshlrev_b64 v[70:71], 11, v[70:71]
	v_ashrrev_i32_e32 v73, 31, v72
	v_cndmask_b32_e64 v80, v80, v135, s[44:45]
	v_lshl_add_u64 v[68:69], v[66:67], 0, v[68:69]
	v_lshl_add_u64 v[70:71], v[66:67], 0, v[70:71]
	v_lshlrev_b64 v[72:73], 11, v[72:73]
	v_lshl_add_u32 v80, v80, 1, v134
	v_lshl_add_u64 v[78:79], v[66:67], 0, v[72:73]
	global_load_dwordx2 v[74:75], v[68:69], off
	global_load_dwordx2 v[72:73], v[70:71], off
	s_nop 0
	global_load_dwordx2 v[70:71], v[76:77], off
	global_load_dwordx2 v[68:69], v[78:79], off
	v_ashrrev_i32_e32 v81, 31, v80
	v_cndmask_b32_e64 v76, 2, 29, s[0:1]
	v_cndmask_b32_e64 v78, 3, 28, s[0:1]
	v_lshlrev_b64 v[80:81], 11, v[80:81]
	v_or_b32_e32 v76, s72, v76
	v_cmp_gt_u32_e64 s[40:41], 5, v101
	v_or_b32_e32 v78, s72, v78
	v_cmp_gt_u32_e64 s[42:43], 6, v101
	v_lshl_add_u64 v[84:85], v[66:67], 0, v[80:81]
	v_cndmask_b32_e64 v80, 5, 26, s[0:1]
	v_cndmask_b32_e64 v76, v76, v135, s[40:41]
	v_cndmask_b32_e64 v78, v78, v135, s[42:43]
	v_or_b32_e32 v80, s72, v80
	v_cmp_gt_u32_e64 s[46:47], 8, v101
	v_lshl_add_u32 v76, v76, 1, v134
	v_lshl_add_u32 v78, v78, 1, v134
	v_cndmask_b32_e64 v80, v80, v135, s[46:47]
	v_cndmask_b32_e64 v88, 8, 23, s[0:1]
	v_ashrrev_i32_e32 v77, 31, v76
	v_ashrrev_i32_e32 v79, 31, v78
	v_lshl_add_u32 v80, v80, 1, v134
	v_or_b32_e32 v88, s72, v88
	v_cmp_gt_u32_e64 s[52:53], 11, v101
	v_lshlrev_b64 v[76:77], 11, v[76:77]
	v_lshlrev_b64 v[78:79], 11, v[78:79]
	v_ashrrev_i32_e32 v81, 31, v80
	v_cndmask_b32_e64 v88, v88, v135, s[52:53]
	v_lshl_add_u64 v[76:77], v[66:67], 0, v[76:77]
	v_lshl_add_u64 v[78:79], v[66:67], 0, v[78:79]
	v_lshlrev_b64 v[80:81], 11, v[80:81]
	v_lshl_add_u32 v88, v88, 1, v134
	v_lshl_add_u64 v[86:87], v[66:67], 0, v[80:81]
	global_load_dwordx2 v[82:83], v[76:77], off
	global_load_dwordx2 v[80:81], v[78:79], off
	s_nop 0
	global_load_dwordx2 v[78:79], v[84:85], off
	global_load_dwordx2 v[76:77], v[86:87], off
	v_ashrrev_i32_e32 v89, 31, v88
	v_cndmask_b32_e64 v84, 6, 25, s[0:1]
	v_cndmask_b32_e64 v86, 7, 24, s[0:1]
	v_lshlrev_b64 v[88:89], 11, v[88:89]
	v_or_b32_e32 v84, s72, v84
	v_cmp_gt_u32_e64 s[48:49], 9, v101
	v_or_b32_e32 v86, s72, v86
	v_cmp_gt_u32_e64 s[50:51], 10, v101
	v_lshl_add_u64 v[92:93], v[66:67], 0, v[88:89]
	v_cndmask_b32_e64 v88, 9, 22, s[0:1]
	v_cndmask_b32_e64 v84, v84, v135, s[48:49]
	v_cndmask_b32_e64 v86, v86, v135, s[50:51]
	v_or_b32_e32 v88, s72, v88
	v_cmp_gt_u32_e64 s[54:55], 12, v101
	v_lshl_add_u32 v84, v84, 1, v134
	v_lshl_add_u32 v86, v86, 1, v134
	v_cndmask_b32_e64 v88, v88, v135, s[54:55]
	v_cndmask_b32_e64 v96, 12, 19, s[0:1]
	v_ashrrev_i32_e32 v85, 31, v84
	v_ashrrev_i32_e32 v87, 31, v86
	v_lshl_add_u32 v88, v88, 1, v134
	v_or_b32_e32 v96, s72, v96
	v_cmp_gt_u32_e64 s[60:61], 15, v101
	v_lshlrev_b64 v[84:85], 11, v[84:85]
	v_lshlrev_b64 v[86:87], 11, v[86:87]
	v_ashrrev_i32_e32 v89, 31, v88
	v_cndmask_b32_e64 v96, v96, v135, s[60:61]
	v_lshl_add_u64 v[84:85], v[66:67], 0, v[84:85]
	v_lshl_add_u64 v[86:87], v[66:67], 0, v[86:87]
	v_lshlrev_b64 v[88:89], 11, v[88:89]
	v_lshl_add_u32 v96, v96, 1, v134
	v_lshl_add_u64 v[94:95], v[66:67], 0, v[88:89]
	global_load_dwordx2 v[90:91], v[84:85], off
	global_load_dwordx2 v[88:89], v[86:87], off
	s_nop 0
	global_load_dwordx2 v[86:87], v[92:93], off
	global_load_dwordx2 v[84:85], v[94:95], off
	v_ashrrev_i32_e32 v97, 31, v96
	v_cndmask_b32_e64 v92, 10, 21, s[0:1]
	v_cndmask_b32_e64 v94, 11, 20, s[0:1]
	v_lshlrev_b64 v[96:97], 11, v[96:97]
	v_or_b32_e32 v92, s72, v92
	v_cmp_gt_u32_e64 s[56:57], 13, v101
	v_or_b32_e32 v94, s72, v94
	v_cmp_gt_u32_e64 s[58:59], 14, v101
	v_lshl_add_u64 v[102:103], v[66:67], 0, v[96:97]
	v_cndmask_b32_e64 v96, 13, 18, s[0:1]
	v_cndmask_b32_e64 v92, v92, v135, s[56:57]
	v_cndmask_b32_e64 v94, v94, v135, s[58:59]
	v_or_b32_e32 v96, s72, v96
	v_cmp_gt_u32_e64 s[62:63], 16, v101
	v_lshl_add_u32 v92, v92, 1, v134
	v_lshl_add_u32 v94, v94, 1, v134
	v_cndmask_b32_e64 v96, v96, v135, s[62:63]
	v_ashrrev_i32_e32 v93, 31, v92
	v_ashrrev_i32_e32 v95, 31, v94
	v_lshl_add_u32 v96, v96, 1, v134
	v_lshlrev_b64 v[92:93], 11, v[92:93]
	v_lshlrev_b64 v[94:95], 11, v[94:95]
	v_ashrrev_i32_e32 v97, 31, v96
	v_lshl_add_u64 v[92:93], v[66:67], 0, v[92:93]
	v_lshl_add_u64 v[94:95], v[66:67], 0, v[94:95]
	v_lshlrev_b64 v[96:97], 11, v[96:97]
	v_lshl_add_u64 v[104:105], v[66:67], 0, v[96:97]
	global_load_dwordx2 v[98:99], v[92:93], off
; __device__ __forceinline__ void lru_carries(const Args& a, LAS float* carry, int tt, const Tile& T) {
;     ...
;     f32x2 sm[33];
; #pragma unroll
;     for (int p = 0; p < 33; ++p) {
;         const int pc = p < pos ? p : 0;
;         int t2;
;         if (pc < 2) t2 = 128 + 2 * T.b + (dir ? 1 - pc : pc); else t2 = 32 * T.b + (dir ? 31 - (pc - 2) : (pc - 2));
;         sm[p] = *(const f32x2*)(SUM + ((size_t)(t2 * 2 + dir) * 256 + ch) * 2);
;     }
	global_load_dwordx2 v[96:97], v[94:95], off
	s_nop 0
	global_load_dwordx2 v[94:95], v[102:103], off
	global_load_dwordx2 v[92:93], v[104:105], off
	v_cndmask_b32_e64 v102, 14, 17, s[0:1]
	v_cndmask_b32_e64 v104, 15, 16, s[0:1]
	v_cndmask_b32_e64 v106, 16, 15, s[0:1]
	v_cndmask_b32_e64 v108, 17, 14, s[0:1]
	v_or_b32_e32 v102, s72, v102
	v_cmp_gt_u32_e64 s[64:65], 17, v101
	v_or_b32_e32 v104, s72, v104
	v_cmp_gt_u32_e64 s[66:67], 18, v101
	v_or_b32_e32 v106, s72, v106
	v_cmp_gt_u32_e64 s[68:69], 19, v101
	v_or_b32_e32 v108, s72, v108
	v_cmp_gt_u32_e64 s[70:71], 20, v101
	v_cndmask_b32_e64 v102, v102, v135, s[64:65]
	v_cndmask_b32_e64 v104, v104, v135, s[66:67]
	v_cndmask_b32_e64 v106, v106, v135, s[68:69]
	v_cndmask_b32_e64 v108, v108, v135, s[70:71]
	v_lshl_add_u32 v102, v102, 1, v134
	v_lshl_add_u32 v104, v104, 1, v134
	v_lshl_add_u32 v106, v106, 1, v134
	v_lshl_add_u32 v108, v108, 1, v134
	v_ashrrev_i32_e32 v103, 31, v102
	v_ashrrev_i32_e32 v105, 31, v104
	v_ashrrev_i32_e32 v107, 31, v106
	v_ashrrev_i32_e32 v109, 31, v108
	v_lshlrev_b64 v[102:103], 11, v[102:103]
	v_lshlrev_b64 v[104:105], 11, v[104:105]
	v_lshlrev_b64 v[106:107], 11, v[106:107]
	v_lshlrev_b64 v[108:109], 11, v[108:109]
	v_lshl_add_u64 v[102:103], v[66:67], 0, v[102:103]
	v_lshl_add_u64 v[104:105], v[66:67], 0, v[104:105]
	v_lshl_add_u64 v[106:107], v[66:67], 0, v[106:107]
	v_lshl_add_u64 v[108:109], v[66:67], 0, v[108:109]
	global_load_dwordx2 v[102:103], v[102:103], off
	s_nop 0
	global_load_dwordx2 v[104:105], v[104:105], off
	s_nop 0
	global_load_dwordx2 v[106:107], v[106:107], off
	s_nop 0
	global_load_dwordx2 v[108:109], v[108:109], off
	v_cndmask_b32_e64 v110, 18, 13, s[0:1]
	v_cndmask_b32_e64 v112, 19, 12, s[0:1]
	v_cndmask_b32_e64 v114, 20, 11, s[0:1]
	v_cndmask_b32_e64 v116, 21, 10, s[0:1]
	v_or_b32_e32 v110, s72, v110
	v_cmp_gt_u32_e64 s[74:75], 21, v101
	v_or_b32_e32 v112, s72, v112
	v_cmp_gt_u32_e64 s[76:77], 22, v101
	v_or_b32_e32 v114, s72, v114
	v_cmp_gt_u32_e64 s[78:79], 23, v101
	v_or_b32_e32 v116, s72, v116
	v_cmp_gt_u32_e64 s[80:81], 24, v101
	v_cndmask_b32_e64 v110, v110, v135, s[74:75]
	v_cndmask_b32_e64 v112, v112, v135, s[76:77]
	v_cndmask_b32_e64 v114, v114, v135, s[78:79]
	v_cndmask_b32_e64 v116, v116, v135, s[80:81]
	v_lshl_add_u32 v110, v110, 1, v134
	v_lshl_add_u32 v112, v112, 1, v134
	v_lshl_add_u32 v114, v114, 1, v134
	v_lshl_add_u32 v116, v116, 1, v134
	v_ashrrev_i32_e32 v111, 31, v110
	v_ashrrev_i32_e32 v113, 31, v112
	v_ashrrev_i32_e32 v115, 31, v114
	v_ashrrev_i32_e32 v117, 31, v116
	v_lshlrev_b64 v[110:111], 11, v[110:111]
	v_lshlrev_b64 v[112:113], 11, v[112:113]
	v_lshlrev_b64 v[114:115], 11, v[114:115]
	v_lshlrev_b64 v[116:117], 11, v[116:117]
	v_lshl_add_u64 v[110:111], v[66:67], 0, v[110:111]
	v_lshl_add_u64 v[112:113], v[66:67], 0, v[112:113]
	v_lshl_add_u64 v[114:115], v[66:67], 0, v[114:115]
	v_lshl_add_u64 v[116:117], v[66:67], 0, v[116:117]
	global_load_dwordx2 v[110:111], v[110:111], off
	s_nop 0
	global_load_dwordx2 v[112:113], v[112:113], off
	s_nop 0
	global_load_dwordx2 v[114:115], v[114:115], off
	s_nop 0
	global_load_dwordx2 v[116:117], v[116:117], off
	v_cndmask_b32_e64 v118, 22, 9, s[0:1]
	v_cndmask_b32_e64 v120, 23, 8, s[0:1]
	v_cndmask_b32_e64 v122, 24, 7, s[0:1]
	v_cndmask_b32_e64 v124, 25, 6, s[0:1]
	v_or_b32_e32 v118, s72, v118
	s_mov_b32 s17, s82
	v_cmp_gt_u32_e64 s[82:83], 25, v101
	v_or_b32_e32 v120, s72, v120
	v_cmp_gt_u32_e64 s[84:85], 26, v101
	v_or_b32_e32 v122, s72, v122
	v_cmp_gt_u32_e64 s[86:87], 27, v101
	v_or_b32_e32 v124, s72, v124
	v_cmp_gt_u32_e64 s[88:89], 28, v101
	v_cndmask_b32_e64 v118, v118, v135, s[82:83]
	v_cndmask_b32_e64 v120, v120, v135, s[84:85]
	v_cndmask_b32_e64 v122, v122, v135, s[86:87]
	v_cndmask_b32_e64 v124, v124, v135, s[88:89]
	v_lshl_add_u32 v118, v118, 1, v134
	v_lshl_add_u32 v120, v120, 1, v134
	v_lshl_add_u32 v122, v122, 1, v134
	v_lshl_add_u32 v124, v124, 1, v134
	v_ashrrev_i32_e32 v119, 31, v118
	v_ashrrev_i32_e32 v121, 31, v120
	v_ashrrev_i32_e32 v123, 31, v122
	v_ashrrev_i32_e32 v125, 31, v124
	v_lshlrev_b64 v[118:119], 11, v[118:119]
	v_lshlrev_b64 v[120:121], 11, v[120:121]
	v_lshlrev_b64 v[122:123], 11, v[122:123]
	v_lshlrev_b64 v[124:125], 11, v[124:125]
	v_lshl_add_u64 v[118:119], v[66:67], 0, v[118:119]
	v_lshl_add_u64 v[120:121], v[66:67], 0, v[120:121]
	v_lshl_add_u64 v[122:123], v[66:67], 0, v[122:123]
	v_lshl_add_u64 v[124:125], v[66:67], 0, v[124:125]
	global_load_dwordx2 v[118:119], v[118:119], off
	s_nop 0
	global_load_dwordx2 v[120:121], v[120:121], off
	s_nop 0
	global_load_dwordx2 v[122:123], v[122:123], off
	s_nop 0
	global_load_dwordx2 v[124:125], v[124:125], off
	v_cndmask_b32_e64 v126, 26, 5, s[0:1]
	v_cndmask_b32_e64 v128, 27, 4, s[0:1]
	v_cndmask_b32_e64 v130, 28, 3, s[0:1]
	v_cndmask_b32_e64 v132, 29, 2, s[0:1]
	v_or_b32_e32 v126, s72, v126
	v_cmp_gt_u32_e64 s[90:91], 29, v101
	v_or_b32_e32 v128, s72, v128
	v_cmp_gt_u32_e64 s[92:93], 30, v101
	v_or_b32_e32 v130, s72, v130
	v_cmp_gt_u32_e64 s[94:95], 31, v101
	v_or_b32_e32 v132, s72, v132
	v_cmp_gt_u32_e64 s[96:97], 32, v101
	v_cndmask_b32_e64 v126, v126, v135, s[90:91]
	v_cndmask_b32_e64 v128, v128, v135, s[92:93]
	v_cndmask_b32_e64 v130, v130, v135, s[94:95]
	v_cndmask_b32_e64 v132, v132, v135, s[96:97]
	v_lshl_add_u32 v126, v126, 1, v134
	v_lshl_add_u32 v128, v128, 1, v134
	v_lshl_add_u32 v130, v130, 1, v134
	v_lshl_add_u32 v132, v132, 1, v134
	v_ashrrev_i32_e32 v127, 31, v126
	v_ashrrev_i32_e32 v129, 31, v128
	v_ashrrev_i32_e32 v131, 31, v130
	v_ashrrev_i32_e32 v133, 31, v132
	v_lshlrev_b64 v[126:127], 11, v[126:127]
	v_lshlrev_b64 v[128:129], 11, v[128:129]
	v_lshlrev_b64 v[130:131], 11, v[130:131]
	v_lshlrev_b64 v[132:133], 11, v[132:133]
	v_cndmask_b32_e64 v136, 30, 1, s[0:1]
	v_lshl_add_u64 v[126:127], v[66:67], 0, v[126:127]
	v_lshl_add_u64 v[128:129], v[66:67], 0, v[128:129]
	v_lshl_add_u64 v[130:131], v[66:67], 0, v[130:131]
	v_lshl_add_u64 v[132:133], v[66:67], 0, v[132:133]
	v_or_b32_e32 v136, s72, v136
	v_cmp_gt_u32_e64 s[0:1], 33, v101
	global_load_dwordx2 v[126:127], v[126:127], off
	s_nop 0
	global_load_dwordx2 v[128:129], v[128:129], off
	s_nop 0
	global_load_dwordx2 v[130:131], v[130:131], off
	s_nop 0
	global_load_dwordx2 v[132:133], v[132:133], off
	v_cndmask_b32_e64 v135, v136, v135, s[0:1]
	v_lshl_add_u32 v134, v135, 1, v134
	v_ashrrev_i32_e32 v135, 31, v134
	v_lshlrev_b64 v[134:135], 11, v[134:135]
	v_lshl_add_u64 v[66:67], v[66:67], 0, v[134:135]
	global_load_dwordx2 v[66:67], v[66:67], off
	s_waitcnt vmcnt(0)
; #define LAS __attribute__((address_space(3)))
; __device__ __forceinline__ int opaque_tid() { int t = threadIdx.x; asm volatile("" : "+v"(t)); return t; }
; template <int NROWS, int STRIDE>
; __device__ __forceinline__ void fill_tile(LAS bf16_t* dst, const bf16_t* PX, const Tile& T, int tok0, int col) {
;     const int tid = opaque_tid();
;     constexpr int NIT = (NROWS * 32 + NTHREADS - 1) / NTHREADS;
;     u32x4 v[NIT];
; #pragma unroll
;     for (int it = 0; it < NIT; ++it) {
;         const int idx = min(tid + NTHREADS * it, NROWS * 32 - 1), r = idx >> 5, vec = idx & 31, tg = T.t0 + tok0 + r, tgc = min(max(tg, 0), T.seqlen - 1);
;         v[it] = *(const u32x4*)(PX + (size_t)(T.rowbase + tgc) * DIN + col + vec * 8);
;     }
; #pragma unroll
;     for (int it = 0; it < NIT; ++it) {
;         const int idx = tid + NTHREADS * it, r = idx >> 5, vec = idx & 31, tg = T.t0 + tok0 + r;
;         const bool ok = tg >= 0 && tg < T.seqlen;
;         u32x4 o = v[it]; if (!ok) o = (u32x4){0u, 0u, 0u, 0u};
;         if (idx < NROWS * 32) *(LAS u32x4*)(dst + r * STRIDE + vec * 8) = o;
;     }
; __device__ __forceinline__ void lru_carries(const Args& a, LAS float* carry, int tt, const Tile& T) {
;     ...
; #pragma unroll
;     for (int p = 0; p < 33; ++p) if (p < pos) hst = sm[p][0] * hst + sm[p][1];
;     carry[tid] = hst;
	v_fmac_f32_e32 v75, 0, v74
	v_cmp_ne_u32_e32 vcc, 0, v101
	s_lshl_b32 s72, s17, 7
	s_and_b32 s72, s35, s72
	v_cndmask_b32_e32 v74, 0, v75, vcc
	v_fmac_f32_e32 v73, v72, v74
	v_cndmask_b32_e64 v72, v74, v73, s[4:5]
	v_fmac_f32_e32 v71, v70, v72
	v_cndmask_b32_e64 v70, v72, v71, s[36:37]
	v_fmac_f32_e32 v69, v68, v70
	v_cndmask_b32_e64 v68, v69, v70, s[38:39]
	v_fmac_f32_e32 v83, v82, v68
	v_cndmask_b32_e64 v68, v83, v68, s[40:41]
	v_fmac_f32_e32 v81, v80, v68
	v_cndmask_b32_e64 v68, v81, v68, s[42:43]
	v_fmac_f32_e32 v79, v78, v68
	v_cndmask_b32_e64 v68, v79, v68, s[44:45]
	v_fmac_f32_e32 v77, v76, v68
	v_cndmask_b32_e64 v68, v77, v68, s[46:47]
	v_fmac_f32_e32 v91, v90, v68
	v_cndmask_b32_e64 v68, v91, v68, s[48:49]
	v_fmac_f32_e32 v89, v88, v68
	v_cndmask_b32_e64 v68, v89, v68, s[50:51]
	v_fmac_f32_e32 v87, v86, v68
	v_cndmask_b32_e64 v68, v87, v68, s[52:53]
	v_fmac_f32_e32 v85, v84, v68
	v_cndmask_b32_e64 v68, v85, v68, s[54:55]
	v_fmac_f32_e32 v99, v98, v68
	v_cndmask_b32_e64 v68, v99, v68, s[56:57]
	v_fmac_f32_e32 v97, v96, v68
	v_cndmask_b32_e64 v68, v97, v68, s[58:59]
	v_fmac_f32_e32 v95, v94, v68
	v_cndmask_b32_e64 v68, v95, v68, s[60:61]
	v_fmac_f32_e32 v93, v92, v68
	v_cndmask_b32_e64 v68, v93, v68, s[62:63]
	v_fmac_f32_e32 v103, v102, v68
	v_cndmask_b32_e64 v68, v103, v68, s[64:65]
	v_fmac_f32_e32 v105, v104, v68
	v_cndmask_b32_e64 v68, v105, v68, s[66:67]
	v_fmac_f32_e32 v107, v106, v68
	v_cndmask_b32_e64 v68, v107, v68, s[68:69]
	v_fmac_f32_e32 v109, v108, v68
	v_cndmask_b32_e64 v68, v109, v68, s[70:71]
	v_fmac_f32_e32 v111, v110, v68
	v_cndmask_b32_e64 v68, v111, v68, s[74:75]
	v_fmac_f32_e32 v113, v112, v68
	v_cndmask_b32_e64 v68, v113, v68, s[76:77]
	v_fmac_f32_e32 v115, v114, v68
	v_cndmask_b32_e64 v68, v115, v68, s[78:79]
	v_fmac_f32_e32 v117, v116, v68
	v_cndmask_b32_e64 v68, v117, v68, s[80:81]
	v_fmac_f32_e32 v119, v118, v68
	v_cndmask_b32_e64 v68, v119, v68, s[82:83]
	v_fmac_f32_e32 v121, v120, v68
	v_cndmask_b32_e64 v68, v121, v68, s[84:85]
	v_fmac_f32_e32 v123, v122, v68
	v_cndmask_b32_e64 v68, v123, v68, s[86:87]
	v_fmac_f32_e32 v125, v124, v68
	v_cndmask_b32_e64 v68, v125, v68, s[88:89]
	v_mov_b32_e32 v95, v0
	s_add_i32 s35, s34, -1
	v_readlane_b32 s38, v254, 7
	s_movk_i32 s53, 0x1000
	s_mov_b32 s16, s17
	v_fmac_f32_e32 v127, v126, v68
	v_cndmask_b32_e64 v68, v127, v68, s[90:91]
	v_fmac_f32_e32 v129, v128, v68
	v_cndmask_b32_e64 v68, v129, v68, s[92:93]
	v_fmac_f32_e32 v131, v130, v68
	v_cndmask_b32_e64 v68, v131, v68, s[94:95]
	v_fmac_f32_e32 v133, v132, v68
	v_cndmask_b32_e64 v68, v133, v68, s[96:97]
	v_fmac_f32_e32 v67, v66, v68
	v_cndmask_b32_e64 v66, v67, v68, s[0:1]
	v_lshl_add_u32 v67, v100, 2, 0
	v_add_u32_e32 v67, 0x21000, v67
	ds_write_b32 v67, v66
	v_readlane_b32 s0, v253, 45
	v_add_u32_e32 v102, 0x200, v95
	v_min_i32_e32 v70, 0xfff, v102
	v_add_u32_e32 v101, 0x400, v95
	v_ashrrev_i32_e32 v66, 5, v70
	v_lshlrev_b32_e32 v70, 4, v70
	v_min_i32_e32 v72, 0xfff, v101
	v_add_u32_e32 v66, s72, v66
	v_and_b32_e32 v206, 0x1f0, v70
	v_ashrrev_i32_e32 v70, 5, v72
	v_max_i32_e32 v66, 0, v66
	v_add_u32_e32 v70, s72, v70
	v_min_u32_e32 v66, s35, v66
	v_readlane_b32 s1, v253, 46
	v_max_i32_e32 v70, 0, v70
	v_add_u32_e32 v68, s73, v66
	v_mov_b64_e32 v[66:67], s[0:1]
	v_min_u32_e32 v70, s35, v70
	v_mad_i64_i32 v[68:69], s[0:1], v68, s24, v[66:67]
	v_add_u32_e32 v70, s73, v70
	v_lshlrev_b32_e32 v72, 4, v72
	v_lshl_add_u64 v[68:69], v[68:69], 0, v[206:207]
	v_mad_i64_i32 v[70:71], s[0:1], v70, s24, v[66:67]
	v_and_b32_e32 v206, 0x1f0, v72
	v_lshl_add_u64 v[70:71], v[70:71], 0, v[206:207]
	v_add_u32_e32 v100, 0x600, v95
	s_nop 0
	s_nop 0
	v_min_i32_e32 v70, 0xfff, v100
	v_add_u32_e32 v99, 0x800, v95
	v_ashrrev_i32_e32 v68, 5, v70
	v_lshlrev_b32_e32 v70, 4, v70
	v_min_i32_e32 v72, 0xfff, v99
	v_add_u32_e32 v68, s72, v68
	v_and_b32_e32 v206, 0x1f0, v70
	v_ashrrev_i32_e32 v70, 5, v72
	v_max_i32_e32 v68, 0, v68
	v_add_u32_e32 v70, s72, v70
	v_min_u32_e32 v68, s35, v68
	v_max_i32_e32 v70, 0, v70
	v_add_u32_e32 v68, s73, v68
	v_min_u32_e32 v70, s35, v70
	v_mad_i64_i32 v[68:69], s[0:1], v68, s24, v[66:67]
	v_add_u32_e32 v70, s73, v70
	v_lshlrev_b32_e32 v72, 4, v72
	v_lshl_add_u64 v[68:69], v[68:69], 0, v[206:207]
	v_mad_i64_i32 v[70:71], s[0:1], v70, s24, v[66:67]
	v_and_b32_e32 v206, 0x1f0, v72
	v_lshl_add_u64 v[70:71], v[70:71], 0, v[206:207]
	v_add_u32_e32 v98, 0xa00, v95
	s_nop 0
	s_nop 0
	v_min_i32_e32 v70, 0xfff, v98
	v_add_u32_e32 v97, 0xc00, v95
	v_ashrrev_i32_e32 v68, 5, v70
	v_lshlrev_b32_e32 v70, 4, v70
	v_min_i32_e32 v72, 0xfff, v97
	v_add_u32_e32 v68, s72, v68
	v_and_b32_e32 v206, 0x1f0, v70
	v_ashrrev_i32_e32 v70, 5, v72
	v_max_i32_e32 v68, 0, v68
	v_add_u32_e32 v70, s72, v70
	v_min_u32_e32 v68, s35, v68
	v_max_i32_e32 v70, 0, v70
	v_add_u32_e32 v68, s73, v68
	v_min_u32_e32 v70, s35, v70
	v_mad_i64_i32 v[68:69], s[0:1], v68, s24, v[66:67]
	v_add_u32_e32 v70, s73, v70
	v_lshlrev_b32_e32 v72, 4, v72
	v_lshl_add_u64 v[68:69], v[68:69], 0, v[206:207]
	v_mad_i64_i32 v[70:71], s[0:1], v70, s24, v[66:67]
	v_and_b32_e32 v206, 0x1f0, v72
	v_lshl_add_u64 v[70:71], v[70:71], 0, v[206:207]
	v_add_u32_e32 v96, 0xe00, v95
	s_nop 0
	s_nop 0
	s_nop 0
	v_min_i32_e32 v68, 0xfff, v96
	v_ashrrev_i32_e32 v69, 5, v68
	v_add_u32_e32 v69, s72, v69
	v_max_i32_e32 v69, 0, v69
	v_min_u32_e32 v69, s35, v69
	v_add_u32_e32 v69, s73, v69
	v_lshlrev_b32_e32 v68, 4, v68
	v_mad_i64_i32 v[66:67], s[0:1], v69, s24, v[66:67]
	v_and_b32_e32 v206, 0x1f0, v68
	v_lshl_add_u64 v[66:67], v[66:67], 0, v[206:207]
	s_nop 0
	v_lshlrev_b32_e32 v94, 3, v95
	v_and_b32_e32 v103, 0xf8, v94
	v_lshl_add_u32 v94, v103, 1, s38
	v_cmp_gt_i32_e32 vcc, s53, v95
	s_and_saveexec_b64 s[0:1], vcc
	s_cbranch_execz .LBB0_527
	v_ashrrev_i32_e32 v108, 5, v95
	v_add_u32_e32 v110, s72, v108
	v_max_i32_e32 v104, 0, v110
	v_readlane_b32 s4, v253, 45
	v_min_u32_e32 v104, s35, v104
	v_readlane_b32 s5, v253, 46
	v_add_u32_e32 v106, s73, v104
	v_lshlrev_b32_e32 v206, 1, v103
	v_mov_b64_e32 v[104:105], s[4:5]
	v_mad_i64_i32 v[104:105], s[4:5], v106, s24, v[104:105]
	v_lshl_add_u64 v[104:105], v[104:105], 0, v[206:207]
	s_nop 0
	v_cmp_gt_u32_e32 vcc, s34, v110
	v_mad_u64_u32 v[108:109], s[4:5], v108, s29, v[94:95]
	s_waitcnt vmcnt(0)
	v_cndmask_b32_e32 v107, 0, v107, vcc
	v_cndmask_b32_e32 v106, 0, v106, vcc
	v_cndmask_b32_e32 v105, 0, v105, vcc
	v_cndmask_b32_e32 v104, 0, v104, vcc
	s_nop 0
; #define LAS __attribute__((address_space(3)))
; template <int NROWS, int STRIDE>
; __device__ __forceinline__ void fill_tile(LAS bf16_t* dst, const bf16_t* PX, const Tile& T, int tok0, int col) {
;     ...
; #pragma unroll
;     for (int it = 0; it < NIT; ++it) {
;         const int idx = tid + NTHREADS * it, r = idx >> 5, vec = idx & 31, tg = T.t0 + tok0 + r;
;         const bool ok = tg >= 0 && tg < T.seqlen;
;         u32x4 o = v[it]; if (!ok) o = (u32x4){0u, 0u, 0u, 0u};
;         if (idx < NROWS * 32) *(LAS u32x4*)(dst + r * STRIDE + vec * 8) = o;
;     }
.LBB0_527:
	s_or_b64 exec, exec, s[0:1]
	v_cmp_gt_i32_e32 vcc, s24, v95
	s_and_saveexec_b64 s[0:1], vcc
	v_readlane_b32 s58, v254, 59
	v_readlane_b32 s44, v255, 33
	v_readlane_b32 s46, v255, 35
	v_readlane_b32 s59, v254, 60
	v_readlane_b32 s52, v255, 31
	v_readlane_b32 s54, v255, 32
	v_readlane_b32 s45, v255, 34
	v_readlane_b32 s47, v255, 36
	s_cbranch_execz .LBB0_529
	v_ashrrev_i32_e32 v104, 5, v102
	v_mad_u64_u32 v[102:103], s[4:5], v104, s29, v[94:95]
	v_add_u32_e32 v103, s72, v104
	v_cmp_gt_u32_e32 vcc, s34, v103
	s_waitcnt vmcnt(6)
	s_nop 0
	v_cndmask_b32_e32 v93, 0, v93, vcc
	v_cndmask_b32_e32 v92, 0, v92, vcc
	v_cndmask_b32_e32 v91, 0, v91, vcc
	v_cndmask_b32_e32 v90, 0, v90, vcc
	s_nop 0
.LBB0_529:
	s_or_b64 exec, exec, s[0:1]
	s_movk_i32 s0, 0xc00
	v_cmp_gt_i32_e32 vcc, s0, v95
	s_and_saveexec_b64 s[0:1], vcc
	v_readlane_b32 s92, v254, 57
	s_mov_b32 s97, s28
	v_readlane_b32 s95, v254, 55
	v_readlane_b32 s96, v254, 56
	v_readlane_b32 s93, v254, 58
	v_readlane_b32 s94, v254, 61
	s_mov_b32 s57, s8
	v_readlane_b32 s90, v255, 22
	s_mov_b64 s[76:77], s[10:11]
	s_mov_b32 s78, s12
	s_mov_b32 s56, s9
	s_mov_b32 s79, s13
	s_mov_b64 s[80:81], s[14:15]
	s_mov_b32 s82, s16
	s_cbranch_execz .LBB0_531
	s_waitcnt vmcnt(6)
	v_ashrrev_i32_e32 v92, 5, v101
	v_mad_u64_u32 v[90:91], s[4:5], v92, s29, v[94:95]
	v_add_u32_e32 v91, s72, v92
	v_cmp_gt_u32_e32 vcc, s34, v91
	s_waitcnt vmcnt(5)
	s_nop 0
	v_cndmask_b32_e32 v85, 0, v85, vcc
	v_cndmask_b32_e32 v84, 0, v84, vcc
	v_cndmask_b32_e32 v83, 0, v83, vcc
	v_cndmask_b32_e32 v82, 0, v82, vcc
	s_nop 0
.LBB0_531:
	s_or_b64 exec, exec, s[0:1]
	s_movk_i32 s0, 0xa00
	v_cmp_gt_i32_e32 vcc, s0, v95
	s_and_saveexec_b64 s[0:1], vcc
	s_cbranch_execz .LBB0_533
	s_waitcnt vmcnt(5)
	v_ashrrev_i32_e32 v82, 5, v100
	v_mad_u64_u32 v[90:91], s[4:5], v82, s29, v[94:95]
	v_add_u32_e32 v82, s72, v82
	v_cmp_gt_u32_e32 vcc, s34, v82
	s_waitcnt vmcnt(4)
	s_nop 0
	v_cndmask_b32_e32 v85, 0, v89, vcc
	v_cndmask_b32_e32 v84, 0, v88, vcc
	v_cndmask_b32_e32 v83, 0, v87, vcc
	v_cndmask_b32_e32 v82, 0, v86, vcc
	s_nop 0
.LBB0_533:
	s_or_b64 exec, exec, s[0:1]
	s_movk_i32 s0, 0x800
	v_cmp_gt_i32_e32 vcc, s0, v95
	s_and_saveexec_b64 s[0:1], vcc
	s_cbranch_execz .LBB0_535
	s_waitcnt vmcnt(5)
	v_ashrrev_i32_e32 v84, 5, v99
	v_mad_u64_u32 v[82:83], s[4:5], v84, s29, v[94:95]
	v_add_u32_e32 v83, s72, v84
	v_cmp_gt_u32_e32 vcc, s34, v83
	s_waitcnt vmcnt(3)
	s_nop 0
	v_cndmask_b32_e32 v77, 0, v77, vcc
	v_cndmask_b32_e32 v76, 0, v76, vcc
	v_cndmask_b32_e32 v75, 0, v75, vcc
	v_cndmask_b32_e32 v74, 0, v74, vcc
	s_nop 0
.LBB0_535:
	s_or_b64 exec, exec, s[0:1]
	s_movk_i32 s0, 0x600
	v_cmp_gt_i32_e32 vcc, s0, v95
	s_and_saveexec_b64 s[0:1], vcc
	s_cbranch_execz .LBB0_537
	s_waitcnt vmcnt(3)
	v_ashrrev_i32_e32 v74, 5, v98
	v_mad_u64_u32 v[82:83], s[4:5], v74, s29, v[94:95]
	v_add_u32_e32 v74, s72, v74
	v_cmp_gt_u32_e32 vcc, s34, v74
	s_waitcnt vmcnt(2)
	s_nop 0
	v_cndmask_b32_e32 v77, 0, v81, vcc
	v_cndmask_b32_e32 v76, 0, v80, vcc
	v_cndmask_b32_e32 v75, 0, v79, vcc
	v_cndmask_b32_e32 v74, 0, v78, vcc
	s_nop 0
.LBB0_537:
	s_or_b64 exec, exec, s[0:1]
	s_movk_i32 s0, 0x400
	v_cmp_gt_i32_e32 vcc, s0, v95
	s_and_saveexec_b64 s[0:1], vcc
	s_cbranch_execz .LBB0_539
	s_waitcnt vmcnt(3)
	v_ashrrev_i32_e32 v76, 5, v97
	v_mad_u64_u32 v[74:75], s[4:5], v76, s29, v[94:95]
	v_add_u32_e32 v75, s72, v76
	v_cmp_gt_u32_e32 vcc, s34, v75
	s_waitcnt vmcnt(1)
	s_nop 0
	v_cndmask_b32_e32 v73, 0, v73, vcc
	v_cndmask_b32_e32 v72, 0, v72, vcc
	v_cndmask_b32_e32 v71, 0, v71, vcc
	v_cndmask_b32_e32 v70, 0, v70, vcc
	s_nop 0
.LBB0_539:
	s_or_b64 exec, exec, s[0:1]
	s_movk_i32 s0, 0x200
	v_cmp_gt_i32_e32 vcc, s0, v95
	s_and_saveexec_b64 s[0:1], vcc
	s_cbranch_execz .LBB0_541
	s_waitcnt vmcnt(1)
	v_ashrrev_i32_e32 v72, 5, v96
	v_mad_u64_u32 v[70:71], s[4:5], v72, s29, v[94:95]
	v_add_u32_e32 v71, s72, v72
	v_cmp_gt_u32_e32 vcc, s34, v71
	s_waitcnt vmcnt(0)
	s_nop 0
	v_cndmask_b32_e32 v69, 0, v69, vcc
	v_cndmask_b32_e32 v68, 0, v68, vcc
	v_cndmask_b32_e32 v67, 0, v67, vcc
	v_cndmask_b32_e32 v66, 0, v66, vcc
	s_nop 0

; __device__ __forceinline__ void lru_conv_tile(const Args& a, LAS bf16_t* cxb, int l, const Tile& T) {
;     ...
;     for (int i = 0; i < 11; ++i) { const int tg = T.t0 + grp * 8 + i - 2, tgc = min(max(tg, 0), T.seqlen - 1); raw[i] = *(const u32x4*)(PX + (size_t)(T.rowbase + tgc) * DIN + c0); }
; template <int MODE>
; __device__ __forceinline__ void lru_unit(const Args& a, LAS unsigned char* lds, int l, int tt) {
;     ...
;     bf16x8 Bw0[2][2][2], Bw1[2][2][2];
; #pragma unroll
;     for (int g = 0; g < 2; ++g)
; #pragma unroll
;         for (int nt = 0; nt < 2; ++nt)
; #pragma unroll
;             for (int ks = 0; ks < 2; ++ks) {
;                 Bw0[g][nt][ks] = *(const bf16x8*)(LW + ((size_t)((((l * 2 + 0) * 2 + g) * 4 + h) * 64 + 32 * nh + 16 * nt + fr)) * 64 + 32 * ks + 8 * fq);
;                 Bw1[g][nt][ks] = *(const bf16x8*)(LW + ((size_t)((((l * 2 + 1) * 2 + g) * 4 + h) * 64 + 32 * nh + 16 * nt + fr)) * 64 + 32 * ks + 8 * fq);
;             }
;     float prm0[2][3], prm1[2][3];
; #pragma unroll
;     for (int nt = 0; nt < 2; ++nt) {
;         const int c = 64 * h + 32 * nh + 16 * nt + fr;
;         prm0[nt][0] = a.in[12][(l * 2 + 0) * 256 + c]; prm0[nt][1] = a.in[14][(l * 2 + 0) * 256 + c]; prm0[nt][2] = a.in[15][(l * 2 + 0) * 256 + c];
;         prm1[nt][0] = a.in[12][(l * 2 + 1) * 256 + c]; prm1[nt][1] = a.in[14][(l * 2 + 1) * 256 + c]; prm1[nt][2] = a.in[15][(l * 2 + 1) * 256 + c];
;     }
;     if (MODE == 1) { lru_carries(a, carry, tt, T); fill_tile<128, CXS>(gyb, (const bf16_t*)(a.ws + WS_PX), T, 0, 256); }
.LBB0_766:
	s_and_b64 vcc, exec, s[0:1]
	s_cbranch_vccz .LBB0_776
	s_lshl_b32 s0, s82, 7
	s_cmpk_lt_i32 s82, 0x80
	s_movk_i32 s1, 0xf000
	s_cselect_b32 s1, s1, 0xffffff00
	s_movk_i32 s4, 0xf80
	v_mov_b32_e32 v2, v0
	s_cselect_b32 s34, s53, 0x100
	s_cselect_b32 s4, s4, 0x80
	s_and_b32 s36, s1, s0
	v_readlane_b32 s28, v252, 43
	v_readfirstlane_b32 s1, v2
	s_and_b32 s5, s1, 0xc0
	s_ashr_i32 s1, s1, 3
	v_and_b32_e32 v66, 15, v2
	s_andn2_b32 s1, s1, 31
	v_or_b32_e32 v12, s1, v66
	v_add_u32_e32 v13, 0x200, v12
	s_or_b32 s35, s5, s56
	v_and_b32_e32 v206, 48, v2
	v_add_u32_e32 v2, s35, v12
	v_add_u32_e32 v4, s35, v13
	s_bitset1_b32 s35, 8
	v_add_u32_e32 v12, s35, v12
	v_add_u32_e32 v14, s35, v13
	s_add_i32 s1, s1, s5
	s_waitcnt lgkmcnt(0)
	v_ashrrev_i32_e32 v3, 31, v2
	v_ashrrev_i32_e32 v5, 31, v4
	v_ashrrev_i32_e32 v13, 31, v12
	v_ashrrev_i32_e32 v15, 31, v14
	v_or_b32_e32 v66, s1, v66
	v_lshlrev_b64 v[6:7], 7, v[2:3]
	v_lshlrev_b64 v[8:9], 7, v[4:5]
	v_or_b32_e32 v2, 16, v2
	v_or_b32_e32 v4, 16, v4
	v_lshlrev_b64 v[16:17], 7, v[12:13]
	v_lshlrev_b64 v[22:23], 7, v[14:15]
	v_or_b32_e32 v12, 16, v12
	v_or_b32_e32 v14, 16, v14
	v_add_u32_e32 v68, s79, v66
	v_readlane_b32 s29, v252, 44
	v_ashrrev_i32_e32 v3, 31, v2
	v_ashrrev_i32_e32 v5, 31, v4
	v_ashrrev_i32_e32 v13, 31, v12
	v_ashrrev_i32_e32 v15, 31, v14
	v_ashrrev_i32_e32 v69, 31, v68
	v_readlane_b32 s60, v254, 23
	v_ashrrev_i32_e32 v67, 31, v66
	v_lshl_add_u64 v[10:11], s[28:29], 0, v[206:207]
	v_lshlrev_b64 v[2:3], 7, v[2:3]
	v_lshlrev_b64 v[4:5], 7, v[4:5]
	v_lshlrev_b64 v[12:13], 7, v[12:13]
	v_lshlrev_b64 v[14:15], 7, v[14:15]
	v_lshlrev_b64 v[68:69], 2, v[68:69]
	v_readlane_b32 s68, v254, 31
	v_readlane_b32 s69, v254, 32
	v_readlane_b32 s72, v254, 35
	v_readlane_b32 s73, v254, 36
	v_readlane_b32 s74, v254, 37
	v_readlane_b32 s75, v254, 38
	v_lshl_add_u64 v[66:67], v[66:67], 0, s[80:81]
	v_lshl_add_u64 v[6:7], v[10:11], 0, v[6:7]
	v_lshl_add_u64 v[8:9], v[10:11], 0, v[8:9]
	v_lshl_add_u64 v[2:3], v[10:11], 0, v[2:3]
	v_lshl_add_u64 v[4:5], v[10:11], 0, v[4:5]
	v_lshl_add_u64 v[16:17], v[10:11], 0, v[16:17]
	v_lshl_add_u64 v[22:23], v[10:11], 0, v[22:23]
	v_lshl_add_u64 v[12:13], v[10:11], 0, v[12:13]
	v_lshl_add_u64 v[10:11], v[10:11], 0, v[14:15]
	v_lshl_add_u64 v[70:71], s[68:69], 0, v[68:69]
	v_lshl_add_u64 v[72:73], s[72:73], 0, v[68:69]
	v_lshl_add_u64 v[68:69], s[74:75], 0, v[68:69]
	v_lshlrev_b64 v[66:67], 2, v[66:67]
	global_load_dwordx4 v[54:57], v[6:7], off
	global_load_dwordx4 v[50:53], v[6:7], off offset:64
	global_load_dwordx4 v[26:29], v[8:9], off
	global_load_dwordx4 v[18:21], v[8:9], off offset:64
	global_load_dwordx4 v[38:41], v[2:3], off
	global_load_dwordx4 v[34:37], v[2:3], off offset:64
	s_nop 0
	global_load_dwordx4 v[6:9], v[4:5], off
	s_nop 0
	global_load_dwordx4 v[2:5], v[4:5], off offset:64
	s_nop 0
	global_load_dwordx4 v[62:65], v[16:17], off
	global_load_dwordx4 v[58:61], v[16:17], off offset:64
	global_load_dwordx4 v[30:33], v[22:23], off
	s_nop 0
	global_load_dwordx4 v[22:25], v[22:23], off offset:64
	s_nop 0
	global_load_dwordx4 v[46:49], v[12:13], off
	global_load_dwordx4 v[42:45], v[12:13], off offset:64
	global_load_dwordx4 v[14:17], v[10:11], off
	s_nop 0
	global_load_dwordx4 v[10:13], v[10:11], off offset:64
	s_nop 0
	global_load_dword v157, v[70:71], off
	global_load_dword v153, v[70:71], off offset:1024
	global_load_dword v155, v[70:71], off offset:64
	global_load_dword v156, v[72:73], off
	global_load_dword v152, v[72:73], off offset:1024
	global_load_dword v154, v[72:73], off offset:64
	global_load_dword v161, v[68:69], off
	global_load_dword v160, v[68:69], off offset:1024
	global_load_dword v159, v[68:69], off offset:64
	v_lshl_add_u64 v[68:69], s[68:69], 0, v[66:67]
	global_load_dword v151, v[68:69], off offset:64
	v_lshl_add_u64 v[68:69], s[72:73], 0, v[66:67]
	v_lshl_add_u64 v[66:67], s[74:75], 0, v[66:67]
	global_load_dword v158, v[66:67], off offset:64
	v_mov_b32_e32 v66, v0
	global_load_dword v150, v[68:69], off offset:64
	s_and_b32 s35, s4, s0
	v_ashrrev_i32_e32 v163, 2, v66
	v_and_b32_e32 v164, -8, v163
	v_add_u32_e32 v162, s35, v164
	v_lshlrev_b32_e32 v67, 3, v66
	v_or_b32_e32 v66, 1, v162
	v_max_i32_e32 v66, 2, v66
	v_or_b32_e32 v68, 2, v162
	v_and_b32_e32 v70, 0xf8, v67
	s_add_i32 s37, s34, -1
	v_add_u32_e32 v66, -2, v66
	v_max_i32_e32 v68, 2, v68
	v_lshlrev_b32_e32 v206, 1, v70
	v_min_u32_e32 v66, s37, v66
	v_add_u32_e32 v68, -2, v68
	v_lshl_add_u64 v[146:147], s[58:59], 0, v[206:207]
	v_add_u32_e32 v66, s36, v66
	v_min_u32_e32 v68, s37, v68
	v_mad_i64_i32 v[66:67], s[0:1], v66, s24, v[146:147]
	v_add_u32_e32 v68, s36, v68
	v_mad_i64_i32 v[68:69], s[0:1], v68, s24, v[146:147]
	global_load_dwordx4 v[142:145], v[66:67], off
	global_load_dwordx4 v[134:137], v[68:69], off
	v_readfirstlane_b32 s98, v0
	v_and_b32_e32 v209, 31, v0
	v_lshlrev_b32_e32 v209, 4, v209
	s_lshr_b32 s98, s98, 2
	s_mul_i32 m0, s98, 0x210
	s_add_i32 m0, m0, 0x10800
	s_add_i32 vcc_lo, s35, s98
	s_add_i32 vcc_lo, vcc_lo, s36
	s_mul_i32 vcc_lo, vcc_lo, s24
	v_readlane_b32 s98, v253, 45
	v_readlane_b32 s99, v253, 46
	s_add_u32 s98, s98, vcc_lo
	s_addc_u32 s99, s99, 0
; __device__ __forceinline__ void lru_conv_tile(const Args& a, LAS bf16_t* cxb, int l, const Tile& T) {
;     ...
;     for (int i = 0; i < 11; ++i) { const int tg = T.t0 + grp * 8 + i - 2, tgc = min(max(tg, 0), T.seqlen - 1); raw[i] = *(const u32x4*)(PX + (size_t)(T.rowbase + tgc) * DIN + c0); }
;     float w[4][8], bias[8], win[4][8];
; #pragma unroll
;     for (int k = 0; k < 4; ++k) { const f32x4 w0 = *(const f32x4*)(caw + k * 256 + c0), w1 = *(const f32x4*)(caw + k * 256 + c0 + 4);
; #pragma unroll
;         for (int e = 0; e < 4; ++e) { w[k][e] = w0[e]; w[k][4 + e] = w1[e]; } }
;     { const f32x4 b0 = *(const f32x4*)(cab + c0), b1 = *(const f32x4*)(cab + c0 + 4);
; #pragma unroll
;       for (int e = 0; e < 4; ++e) { bias[e] = b0[e]; bias[4 + e] = b1[e]; } }
	s_mov_b32 exec_hi, 0
	s_nop 4
	global_load_lds_dwordx4 v209, s[98:99]
	s_add_u32 s98, s98, 0xe00
	s_addc_u32 s99, s99, 0
	s_add_i32 m0, m0, 0x210
	s_nop 0
	global_load_lds_dwordx4 v209, s[98:99]
	s_add_u32 s98, s98, 0xe00
	s_addc_u32 s99, s99, 0
	s_add_i32 m0, m0, 0x210
	s_nop 0
	global_load_lds_dwordx4 v209, s[98:99]
	s_add_u32 s98, s98, 0xe00
	s_addc_u32 s99, s99, 0
	s_add_i32 m0, m0, 0x210
	s_nop 0
	global_load_lds_dwordx4 v209, s[98:99]
	s_add_u32 s98, s98, 0xe00
	s_addc_u32 s99, s99, 0
	s_add_i32 m0, m0, 0x210
	s_nop 0
	global_load_lds_dwordx4 v209, s[98:99]
	s_add_u32 s98, s98, 0xe00
	s_addc_u32 s99, s99, 0
	s_add_i32 m0, m0, 0x210
	s_nop 0
	global_load_lds_dwordx4 v209, s[98:99]
	s_add_u32 s98, s98, 0xe00
	s_addc_u32 s99, s99, 0
	s_add_i32 m0, m0, 0x210
	s_nop 0
	global_load_lds_dwordx4 v209, s[98:99]
	s_add_u32 s98, s98, 0xe00
	s_addc_u32 s99, s99, 0
	s_add_i32 m0, m0, 0x210
	s_nop 0
	global_load_lds_dwordx4 v209, s[98:99]
	s_add_u32 s98, s98, 0xe00
	s_addc_u32 s99, s99, 0
	s_add_i32 m0, m0, 0x210
	s_nop 0
	global_load_lds_dwordx4 v209, s[98:99]
	s_add_u32 s98, s98, 0xe00
	s_addc_u32 s99, s99, 0
	s_add_i32 m0, m0, 0x210
	s_nop 0
	global_load_lds_dwordx4 v209, s[98:99]
	s_add_u32 s98, s98, 0xe00
	s_addc_u32 s99, s99, 0
	s_add_i32 m0, m0, 0x210
	s_nop 0
	global_load_lds_dwordx4 v209, s[98:99]
	s_add_u32 s98, s98, 0xe00
	s_addc_u32 s99, s99, 0
	s_add_i32 m0, m0, 0x210
	s_nop 0
	global_load_lds_dwordx4 v209, s[98:99]
	s_add_u32 s98, s98, 0xe00
	s_addc_u32 s99, s99, 0
	s_add_i32 m0, m0, 0x210
	s_nop 0
	global_load_lds_dwordx4 v209, s[98:99]
	s_add_u32 s98, s98, 0xe00
	s_addc_u32 s99, s99, 0
	s_add_i32 m0, m0, 0x210
	s_nop 0
	global_load_lds_dwordx4 v209, s[98:99]
	s_add_u32 s98, s98, 0xe00
	s_addc_u32 s99, s99, 0
	s_add_i32 m0, m0, 0x210
	s_nop 0
	global_load_lds_dwordx4 v209, s[98:99]
	s_add_u32 s98, s98, 0xe00
	s_addc_u32 s99, s99, 0
	s_add_i32 m0, m0, 0x210
	s_nop 0
	global_load_lds_dwordx4 v209, s[98:99]
	s_mov_b64 exec, -1
	v_or_b32_e32 v66, 3, v162
	v_max_i32_e32 v66, 2, v66
	v_or_b32_e32 v68, 4, v162
	v_add_u32_e32 v66, -2, v66
	v_max_i32_e32 v68, 2, v68
	v_min_u32_e32 v66, s37, v66
	v_add_u32_e32 v68, -2, v68
	v_add_u32_e32 v66, s36, v66
	v_min_u32_e32 v68, s37, v68
	v_mad_i64_i32 v[66:67], s[0:1], v66, s24, v[146:147]
	v_add_u32_e32 v68, s36, v68
	v_mad_i64_i32 v[68:69], s[0:1], v68, s24, v[146:147]
	global_load_dwordx4 v[138:141], v[66:67], off
	global_load_dwordx4 v[130:133], v[68:69], off
	v_or_b32_e32 v66, 5, v162
	v_max_i32_e32 v66, 2, v66
	v_or_b32_e32 v68, 6, v162
	v_add_u32_e32 v66, -2, v66
	v_max_i32_e32 v68, 2, v68
	v_min_u32_e32 v66, s37, v66
	v_add_u32_e32 v68, -2, v68
	v_add_u32_e32 v66, s36, v66
	v_min_u32_e32 v68, s37, v68
	v_mad_i64_i32 v[66:67], s[0:1], v66, s24, v[146:147]
	v_add_u32_e32 v68, s36, v68
	v_mad_i64_i32 v[68:69], s[0:1], v68, s24, v[146:147]
	global_load_dwordx4 v[126:129], v[66:67], off
	global_load_dwordx4 v[122:125], v[68:69], off
	v_or_b32_e32 v66, 7, v162
	v_max_i32_e32 v66, 2, v66
	v_max_i32_e32 v68, -6, v162
	v_add_u32_e32 v66, -2, v66
	v_add_u32_e32 v68, 6, v68
	v_min_u32_e32 v66, s37, v66
	v_min_u32_e32 v68, s37, v68
	v_add_u32_e32 v66, s36, v66
	v_add_u32_e32 v68, s36, v68
	v_mad_i64_i32 v[66:67], s[0:1], v66, s24, v[146:147]
	v_mad_i64_i32 v[68:69], s[0:1], v68, s24, v[146:147]
	global_load_dwordx4 v[118:121], v[66:67], off
	global_load_dwordx4 v[114:117], v[68:69], off
	v_max_i32_e32 v66, -7, v162
	v_max_i32_e32 v68, -8, v162
	v_add_u32_e32 v66, 7, v66
	v_add_u32_e32 v68, 8, v68
	v_min_u32_e32 v66, s37, v66
	v_min_u32_e32 v68, s37, v68
	v_add_u32_e32 v66, s36, v66
	v_add_u32_e32 v68, s36, v68
	v_mad_i64_i32 v[66:67], s[0:1], v66, s24, v[146:147]
	v_mad_i64_i32 v[68:69], s[0:1], v68, s24, v[146:147]
	v_lshlrev_b32_e32 v102, 2, v70
	global_load_dwordx4 v[110:113], v[66:67], off
	global_load_dwordx4 v[106:109], v[68:69], off
	s_nop 0
	global_load_dwordx4 v[66:69], v102, s[44:45] offset:16
	global_load_dwordx4 v[86:89], v102, s[44:45]
	global_load_dwordx4 v[70:73], v102, s[44:45] offset:1040
	global_load_dwordx4 v[90:93], v102, s[44:45] offset:1024
	global_load_dwordx4 v[74:77], v102, s[44:45] offset:2064
	global_load_dwordx4 v[94:97], v102, s[44:45] offset:2048
	global_load_dwordx4 v[78:81], v102, s[44:45] offset:3088
	global_load_dwordx4 v[98:101], v102, s[44:45] offset:3072
	global_load_dwordx4 v[82:85], v102, s[46:47] offset:16
	s_nop 0
	global_load_dwordx4 v[102:105], v102, s[46:47]
	v_cmp_gt_i32_e64 s[0:1], 2, v162
	v_cmp_lt_i32_e32 vcc, 1, v162
	v_readlane_b32 s61, v254, 24
	v_readlane_b32 s62, v254, 25
	v_readlane_b32 s63, v254, 26
	v_readlane_b32 s64, v254, 27
	v_readlane_b32 s65, v254, 28
	v_readlane_b32 s66, v254, 29
	v_readlane_b32 s67, v254, 30
	v_readlane_b32 s70, v254, 33
	v_readlane_b32 s71, v254, 34
	s_and_saveexec_b64 s[4:5], vcc
	s_cbranch_execz .LBB0_769
	v_add_u32_e32 v148, -2, v162
	v_min_u32_e32 v148, s37, v148
	v_add_u32_e32 v148, s36, v148
	v_mad_i64_i32 v[146:147], s[36:37], v148, s24, v[146:147]
	global_load_dwordx4 v[146:149], v[146:147], off
	v_cmp_lt_u32_e32 vcc, s34, v162
	s_andn2_b64 s[0:1], s[0:1], exec
	s_and_b64 s[36:37], vcc, exec
	s_or_b64 s[0:1], s[0:1], s[36:37]
